# NSA window fast path: next-tile index via v_min_i32 instead of cmp+2 mov+cndmask
# baseline (speedup 1.0000x reference)
; #define EXP2F(x) __builtin_amdgcn_exp2f(x)
; template <class MaskF>
; __device__ __forceinline__ void qk64(const bf16x8 (&kq)[8], const bf16x8 (&qf)[2], float scale, MaskF maskf, int lane,
;                                      f32x4 (&st)[4]) {
;   const int q = lane >> 4;
; #pragma unroll
;   for (int kt = 0; kt < 4; ++kt) {
;     f32x4 z = {0.f, 0.f, 0.f, 0.f};
;     z = mfma16(kq[2 * kt], qf[0], z);
;     z = mfma16(kq[2 * kt + 1], qf[1], z);
; #pragma unroll
;     for (int r = 0; r < 4; ++r) st[kt][r] = maskf(kt * 16 + q * 4 + r) ? z[r] * scale : -INFINITY;
;   }
; }
; __device__ __forceinline__ void softmax_update(f32x4 (&st)[4], float& m, float& lsum, f32x4 (&o)[4]) {
;   float mx = -1e30f;
; #pragma unroll
;   for (int kt = 0; kt < 4; ++kt)
; #pragma unroll
;     for (int r = 0; r < 4; ++r) mx = fmaxf(mx, st[kt][r]);
;   mx = fmaxf(mx, __shfl_xor(mx, 16));
;   mx = fmaxf(mx, __shfl_xor(mx, 32));
;   const float mnew = fmaxf(m, mx);
;   const float alpha = EXP2F(m - mnew);
;   float ps = 0.f;
; #pragma unroll
;   for (int kt = 0; kt < 4; ++kt)
; #pragma unroll
;     for (int r = 0; r < 4; ++r) {
;       const float pv = EXP2F(st[kt][r] - mnew);
;       st[kt][r] = pv;
;       ps += pv;
;     }
;   lsum = lsum * alpha + ps;
;   m = mnew;
;   if (__builtin_amdgcn_ballot_w64(alpha != 1.0f)) {
; #pragma unroll
;     for (int dt = 0; dt < 4; ++dt) o[dt] *= alpha;
;   }
.Lnw_fast:
	s_waitcnt vmcnt(15)
	v_mfma_f32_16x16x32_bf16 v[88:91], v[88:91], v[4:7], 0
	s_add_i32 s22, s11, 1
	v_min_i32_e32 v2, s22, v93
	s_waitcnt vmcnt(14)
	v_mfma_f32_16x16x32_bf16 v[84:87], v[84:87], v[8:11], v[88:91]
	s_waitcnt vmcnt(13)
	v_mfma_f32_16x16x32_bf16 v[80:83], v[80:83], v[4:7], 0
	s_waitcnt vmcnt(12)
	v_mfma_f32_16x16x32_bf16 v[76:79], v[76:79], v[8:11], v[80:83]
	s_waitcnt vmcnt(11)
	v_mfma_f32_16x16x32_bf16 v[72:75], v[72:75], v[4:7], 0
	s_waitcnt vmcnt(10)
	v_mfma_f32_16x16x32_bf16 v[68:71], v[68:71], v[8:11], v[72:75]
	s_waitcnt vmcnt(9)
	v_mfma_f32_16x16x32_bf16 v[52:55], v[52:55], v[4:7], 0
	s_waitcnt vmcnt(8)
	v_mfma_f32_16x16x32_bf16 v[44:47], v[44:47], v[8:11], v[52:55]
	v_mov_b32_e32 v92, v98
	v_lshl_add_u32 v2, v2, 6, v0
	v_mul_f32_e32 v99, 0x3e38aa3b, v84
	v_mul_f32_e32 v100, 0x3e38aa3b, v85
	v_mul_f32_e32 v101, 0x3e38aa3b, v86
	v_mul_f32_e32 v102, 0x3e38aa3b, v87
	v_mul_f32_e32 v103, 0x3e38aa3b, v76
	v_mul_f32_e32 v104, 0x3e38aa3b, v77
	v_mul_f32_e32 v105, 0x3e38aa3b, v78
	v_mul_f32_e32 v106, 0x3e38aa3b, v79
	v_mul_f32_e32 v107, 0x3e38aa3b, v68
	v_mul_f32_e32 v108, 0x3e38aa3b, v69
	v_mul_f32_e32 v109, 0x3e38aa3b, v70
	v_mul_f32_e32 v110, 0x3e38aa3b, v71
	v_mul_f32_e32 v111, 0x3e38aa3b, v44
	v_mul_f32_e32 v112, 0x3e38aa3b, v45
	v_mul_f32_e32 v113, 0x3e38aa3b, v46
	v_mul_f32_e32 v114, 0x3e38aa3b, v47
	v_ashrrev_i32_e32 v3, 31, v2
	v_lshlrev_b64 v[44:45], 7, v[2:3]
	v_lshl_add_u64 v[44:45], v[142:143], 0, v[44:45]
	global_load_dwordx4 v[88:91], v[44:45], off
	global_load_dwordx4 v[84:87], v[44:45], off offset:1024
	global_load_dwordx4 v[80:83], v[44:45], off offset:2048
	global_load_dwordx4 v[76:79], v[44:45], off offset:3072
	v_add_co_u32_e32 v44, vcc, s33, v44
	s_nop 1
	v_addc_co_u32_e32 v45, vcc, 0, v45, vcc
	global_load_dwordx4 v[72:75], v[44:45], off
	global_load_dwordx4 v[68:71], v[44:45], off offset:1024
	global_load_dwordx4 v[52:55], v[44:45], off offset:2048
	s_nop 0
	global_load_dwordx4 v[44:47], v[44:45], off offset:3072
	v_max3_f32 v98, v99, s3, v100
	v_max3_f32 v98, v98, v101, v102
	v_max3_f32 v98, v98, v103, v104
	v_max3_f32 v98, v98, v105, v106
	v_max3_f32 v98, v98, v107, v108
	v_max3_f32 v98, v98, v109, v110
	v_max3_f32 v98, v98, v111, v112
	v_max3_f32 v98, v98, v113, v114
	v_mov_b32_e32 v115, v98
	s_nop 1
	v_permlane16_swap_b32_e32 v115, v98
	v_max_f32_e32 v98, v98, v115
	v_mov_b32_e32 v115, v98
	s_nop 1
	v_permlane32_swap_b32_e32 v115, v98
	v_max3_f32 v98, v92, v98, v115
	v_sub_f32_e32 v92, v92, v98
	v_exp_f32_e32 v92, v92
	s_nop 0
	v_cmp_neq_f32_e32 vcc, 1.0, v92
	s_cbranch_vccz .LBB0_102
	v_pk_mul_f32 v[26:27], v[26:27], v[92:93] op_sel_hi:[1,0]
	v_pk_mul_f32 v[24:25], v[24:25], v[92:93] op_sel_hi:[1,0]
	v_pk_mul_f32 v[22:23], v[22:23], v[92:93] op_sel_hi:[1,0]
	v_pk_mul_f32 v[20:21], v[20:21], v[92:93] op_sel_hi:[1,0]
	v_pk_mul_f32 v[18:19], v[18:19], v[92:93] op_sel_hi:[1,0]
	v_pk_mul_f32 v[16:17], v[16:17], v[92:93] op_sel_hi:[1,0]
	v_pk_mul_f32 v[14:15], v[14:15], v[92:93] op_sel_hi:[1,0]
	v_pk_mul_f32 v[12:13], v[12:13], v[92:93] op_sel_hi:[1,0]
	s_branch .LBB0_102
